# GEMM K-loops: block-ending barrier issued four MFMAs early; next block raises priority after its fourth MFMA
# speedup vs baseline: 1.0055x; 1.0055x over previous
; #define PG8_STAGE(bufoff, gbase, voff) do { _Pragma("unroll") for (int _i = 0; _i < 2; ++_i) \
;         __builtin_amdgcn_global_load_lds((const unsigned*)((const char*)(gbase) + (voff)[_i]), (PG8_LAS unsigned*)(lds + (bufoff) + ldsw + _i * 8192), 16, 0, 0); } while (0)
; #define PG8_LDA(dst, b, h) do { _Pragma("unroll") for (int m = 0; m < 4; ++m) _Pragma("unroll") for (int k = 0; k < 2; ++k) dst[m][k] = *(const PG8_LAS bf16x8*)(lds + PG8_SA(b, h) + aoff + m * 2048 + k * 1024); } while (0)
; #define PG8_LDB(dst, b, h) do { _Pragma("unroll") for (int n = 0; n < 2; ++n) _Pragma("unroll") for (int k = 0; k < 2; ++k) dst[n][k] = *(const PG8_LAS bf16x8*)(lds + PG8_SB(b, h) + boff + n * 2048 + k * 1024); } while (0)
; #define PG8_MMA(ai, bj, At, Bt) do { __builtin_amdgcn_s_setprio(1); _Pragma("unroll") for (int m = 0; m < 4; ++m) _Pragma("unroll") for (int n = 0; n < 2; ++n) _Pragma("unroll") for (int k = 0; k < 2; ++k) \
;         acc[ai][bj][m][n] = __builtin_amdgcn_mfma_f32_16x16x32_bf16(Bt[n][k], At[m][k], acc[ai][bj][m][n], 0, 0, 0); __builtin_amdgcn_s_setprio(0); } while (0)
; #define PG8_WAIT_V(n) asm volatile("s_waitcnt vmcnt(" #n ")" ::: "memory")
; #define PG8_WAIT_L(n) asm volatile("s_waitcnt lgkmcnt(" #n ")" ::: "memory")
; #define PG8_BAR __builtin_amdgcn_s_barrier()
; #define PG8_SCHED __builtin_amdgcn_sched_barrier(0)
; template <class Epi, class Sched, bool ALIGN_EPI = false, bool SP2 = false>
; __device__ __forceinline__ void gemm_phase(PG8_LAS unsigned char* lds, const Gemm g, const Sched& S, const Epi& E) {
;     ...
;             const bool last = (t == nt - 2);
;             const char* a1 = cA + (size_t)(t + 1) * kstep;
;             const char* a2 = last ? nA : cA + (size_t)(t + 2) * kstep; const char* b2 = last ? nB : cB + (size_t)(t + 2) * kstep;
;             const char* a3 = a2 + kstep; const char* b3 = b2 + kstep;
;             if (last && has_next) S.a_ready(nxt);
;             if constexpr (SP2) {
;             PG8_LDB(B0, 0, 0); PG8_LDB(B1, 0, 1); PG8_SCHED; PG8_LDA(At, 0, 0); PG8_STAGE(PG8_SA(1, 1), a1 + hstep, voffA);
;             PG8_WAIT_V(8); PG8_WAIT_L(0); PG8_BAR; PG8_MMA(0, 0, At, B0); PG8_MMA(0, 1, At, B1); PG8_BAR; PG8_SCHED;
;             PG8_LDA(At, 0, 1); PG8_STAGE(PG8_SB(0, 0), b2, voffB); PG8_STAGE(PG8_SB(0, 1), b2 + hstep, voffB); PG8_STAGE(PG8_SA(0, 0), a2, voffA);
.LBB0_165:
	s_add_u32 s16, s8, 0xfffc0080
	s_addc_u32 s17, s9, -1
	s_add_i32 s18, 0, 0x10000
	s_cmp_eq_u32 s55, 12
	s_cselect_b32 s43, s14, s17
	s_cselect_b32 s42, s15, s16
	v_add_u32_e32 v0, s18, v194
	s_cselect_b32 s41, s13, s54
	s_cselect_b32 s40, s25, s53
	s_add_i32 s19, 0, 0x14000
	ds_read_b128 v[136:139], v0
	ds_read_b128 v[140:143], v0 offset:1024
	ds_read_b128 v[144:147], v0 offset:2048
	ds_read_b128 v[148:151], v0 offset:3072
	v_add_u32_e32 v0, s19, v194
	ds_read_b128 v[152:155], v0
	ds_read_b128 v[186:189], v0 offset:1024
	ds_read_b128 v[190:193], v0 offset:2048
	ds_read_b128 v[198:201], v0 offset:3072
	v_lshl_add_u64 v[2:3], s[8:9], 0, v[182:183]
	s_add_i32 m0, s45, 0xc000
	ds_read_b128 v[210:213], v196
	ds_read_b128 v[214:217], v196 offset:1024
	ds_read_b128 v[218:221], v196 offset:2048
	ds_read_b128 v[222:225], v196 offset:3072
	ds_read_b128 v[226:229], v196 offset:4096
	ds_read_b128 v[230:233], v196 offset:5120
	ds_read_b128 v[234:237], v196 offset:6144
	ds_read_b128 v[238:241], v196 offset:7168
	global_load_lds_dwordx4 v[2:3], off
	v_lshl_add_u64 v[2:3], s[8:9], 0, v[184:185]
	s_add_i32 m0, s45, 0xe000
	s_nop 0
	global_load_lds_dwordx4 v[2:3], off
	s_waitcnt vmcnt(8)
	s_waitcnt lgkmcnt(0)
	s_barrier
	s_waitcnt lgkmcnt(0)
	v_mfma_f32_16x16x32_bf16 v[132:135], v[136:139], v[210:213], v[132:135]
	v_mfma_f32_16x16x32_bf16 v[128:131], v[144:147], v[210:213], v[128:131]
	v_mfma_f32_16x16x32_bf16 v[124:127], v[136:139], v[218:221], v[124:127]
	v_mfma_f32_16x16x32_bf16 v[120:123], v[144:147], v[218:221], v[120:123]
	s_setprio 1
	v_mfma_f32_16x16x32_bf16 v[116:119], v[136:139], v[226:229], v[116:119]
	v_mfma_f32_16x16x32_bf16 v[112:115], v[144:147], v[226:229], v[112:115]
	v_mfma_f32_16x16x32_bf16 v[108:111], v[136:139], v[234:237], v[108:111]
	v_mfma_f32_16x16x32_bf16 v[104:107], v[144:147], v[234:237], v[104:107]
	v_mfma_f32_16x16x32_bf16 v[132:135], v[140:143], v[214:217], v[132:135]
	v_mfma_f32_16x16x32_bf16 v[128:131], v[148:151], v[214:217], v[128:131]
	v_mfma_f32_16x16x32_bf16 v[124:127], v[140:143], v[222:225], v[124:127]
	v_mfma_f32_16x16x32_bf16 v[120:123], v[148:151], v[222:225], v[120:123]
	v_mfma_f32_16x16x32_bf16 v[116:119], v[140:143], v[230:233], v[116:119]
	v_mfma_f32_16x16x32_bf16 v[112:115], v[148:151], v[230:233], v[112:115]
	v_mfma_f32_16x16x32_bf16 v[108:111], v[140:143], v[238:241], v[108:111]
	v_mfma_f32_16x16x32_bf16 v[104:107], v[148:151], v[238:241], v[104:107]
	s_setprio 0
	s_setprio 1
	v_mfma_f32_16x16x32_bf16 v[84:87], v[152:155], v[210:213], v[84:87]
	v_mfma_f32_16x16x32_bf16 v[76:79], v[190:193], v[210:213], v[76:79]
	v_mfma_f32_16x16x32_bf16 v[68:71], v[152:155], v[218:221], v[68:71]
	v_mfma_f32_16x16x32_bf16 v[64:67], v[190:193], v[218:221], v[64:67]
	v_mfma_f32_16x16x32_bf16 v[52:55], v[152:155], v[226:229], v[52:55]
	v_mfma_f32_16x16x32_bf16 v[48:51], v[190:193], v[226:229], v[48:51]
	v_mfma_f32_16x16x32_bf16 v[44:47], v[152:155], v[234:237], v[44:47]
	v_mfma_f32_16x16x32_bf16 v[40:43], v[190:193], v[234:237], v[40:43]
	v_mfma_f32_16x16x32_bf16 v[84:87], v[186:189], v[214:217], v[84:87]
	v_mfma_f32_16x16x32_bf16 v[76:79], v[198:201], v[214:217], v[76:79]
	v_mfma_f32_16x16x32_bf16 v[68:71], v[186:189], v[222:225], v[68:71]
	v_mfma_f32_16x16x32_bf16 v[64:67], v[198:201], v[222:225], v[64:67]
	s_barrier
	v_mfma_f32_16x16x32_bf16 v[52:55], v[186:189], v[230:233], v[52:55]
	v_mfma_f32_16x16x32_bf16 v[48:51], v[198:201], v[230:233], v[48:51]
	v_mfma_f32_16x16x32_bf16 v[44:47], v[186:189], v[238:241], v[44:47]
	v_mfma_f32_16x16x32_bf16 v[40:43], v[198:201], v[238:241], v[40:43]
	s_setprio 0
	s_add_i32 s16, s18, s44
	v_lshl_add_u64 v[2:3], s[40:41], 0, v[162:163]
	s_mov_b32 m0, s16
	ds_read_b128 v[210:213], v196 offset:16384
	ds_read_b128 v[214:217], v196 offset:17408
	ds_read_b128 v[218:221], v196 offset:18432
	ds_read_b128 v[222:225], v196 offset:19456
	ds_read_b128 v[226:229], v196 offset:20480
	ds_read_b128 v[230:233], v196 offset:21504
	ds_read_b128 v[234:237], v196 offset:22528
	ds_read_b128 v[238:241], v196 offset:23552
	global_load_lds_dwordx4 v[2:3], off
	s_add_i32 m0, s16, 0x2000
	s_add_u32 s16, s40, 0x40000
	v_lshl_add_u64 v[156:157], s[40:41], 0, v[158:159]
	s_addc_u32 s17, s41, 0
	s_add_i32 s18, s19, s44
	global_load_lds_dwordx4 v[156:157], off
	v_lshl_add_u64 v[242:243], s[16:17], 0, v[162:163]
	s_mov_b32 m0, s18
	v_lshl_add_u64 v[244:245], s[42:43], 0, v[160:161]
	global_load_lds_dwordx4 v[242:243], off
	v_lshl_add_u64 v[242:243], s[16:17], 0, v[158:159]
	s_add_i32 m0, s18, 0x2000
	s_nop 0
	global_load_lds_dwordx4 v[242:243], off
	v_lshl_add_u64 v[242:243], s[42:43], 0, v[178:179]
	s_waitcnt vmcnt(6)
	s_waitcnt lgkmcnt(0)
	s_barrier
; #define PG8_STAGE(bufoff, gbase, voff) do { _Pragma("unroll") for (int _i = 0; _i < 2; ++_i) \
;         __builtin_amdgcn_global_load_lds((const unsigned*)((const char*)(gbase) + (voff)[_i]), (PG8_LAS unsigned*)(lds + (bufoff) + ldsw + _i * 8192), 16, 0, 0); } while (0)
; #define PG8_LDA(dst, b, h) do { _Pragma("unroll") for (int m = 0; m < 4; ++m) _Pragma("unroll") for (int k = 0; k < 2; ++k) dst[m][k] = *(const PG8_LAS bf16x8*)(lds + PG8_SA(b, h) + aoff + m * 2048 + k * 1024); } while (0)
; #define PG8_LDB(dst, b, h) do { _Pragma("unroll") for (int n = 0; n < 2; ++n) _Pragma("unroll") for (int k = 0; k < 2; ++k) dst[n][k] = *(const PG8_LAS bf16x8*)(lds + PG8_SB(b, h) + boff + n * 2048 + k * 1024); } while (0)
; #define PG8_MMA(ai, bj, At, Bt) do { __builtin_amdgcn_s_setprio(1); _Pragma("unroll") for (int m = 0; m < 4; ++m) _Pragma("unroll") for (int n = 0; n < 2; ++n) _Pragma("unroll") for (int k = 0; k < 2; ++k) \
;         acc[ai][bj][m][n] = __builtin_amdgcn_mfma_f32_16x16x32_bf16(Bt[n][k], At[m][k], acc[ai][bj][m][n], 0, 0, 0); __builtin_amdgcn_s_setprio(0); } while (0)
; #define PG8_WAIT_V(n) asm volatile("s_waitcnt vmcnt(" #n ")" ::: "memory")
; #define PG8_WAIT_L(n) asm volatile("s_waitcnt lgkmcnt(" #n ")" ::: "memory")
; #define PG8_BAR __builtin_amdgcn_s_barrier()
; #define PG8_SCHED __builtin_amdgcn_sched_barrier(0)
; template <class Epi, class Sched, bool ALIGN_EPI = false, bool SP2 = false>
; __device__ __forceinline__ void gemm_phase(PG8_LAS unsigned char* lds, const Gemm g, const Sched& S, const Epi& E) {
;     ...
;             PG8_WAIT_V(8); PG8_WAIT_L(0); PG8_BAR; PG8_MMA(1, 0, At, B0); PG8_MMA(1, 1, At, B1); PG8_BAR; PG8_SCHED;
;             PG8_LDB(B0, 1, 0); PG8_LDB(B1, 1, 1); PG8_SCHED; PG8_LDA(At, 1, 0); PG8_STAGE(PG8_SA(0, 1), a2 + hstep, voffA);
;             PG8_WAIT_V(8); PG8_WAIT_L(0); PG8_BAR; PG8_MMA(0, 0, At, B0); PG8_MMA(0, 1, At, B1); PG8_BAR; PG8_SCHED;
	s_waitcnt lgkmcnt(0)
	v_mfma_f32_16x16x32_bf16 v[100:103], v[136:139], v[210:213], v[100:103]
	v_mfma_f32_16x16x32_bf16 v[96:99], v[144:147], v[210:213], v[96:99]
	v_mfma_f32_16x16x32_bf16 v[92:95], v[136:139], v[218:221], v[92:95]
	s_mov_b32 m0, s45
	v_mfma_f32_16x16x32_bf16 v[88:91], v[144:147], v[218:221], v[88:91]
	s_setprio 1
	global_load_lds_dwordx4 v[242:243], off
	v_mfma_f32_16x16x32_bf16 v[80:83], v[136:139], v[226:229], v[80:83]
	v_mfma_f32_16x16x32_bf16 v[72:75], v[144:147], v[226:229], v[72:75]
	v_mfma_f32_16x16x32_bf16 v[60:63], v[136:139], v[234:237], v[60:63]
	v_mfma_f32_16x16x32_bf16 v[56:59], v[144:147], v[234:237], v[56:59]
	v_mfma_f32_16x16x32_bf16 v[100:103], v[140:143], v[214:217], v[100:103]
	v_mfma_f32_16x16x32_bf16 v[96:99], v[148:151], v[214:217], v[96:99]
	v_mfma_f32_16x16x32_bf16 v[92:95], v[140:143], v[222:225], v[92:95]
	s_mov_b32 m0, s46
	v_mfma_f32_16x16x32_bf16 v[88:91], v[148:151], v[222:225], v[88:91]
	global_load_lds_dwordx4 v[244:245], off
	v_mfma_f32_16x16x32_bf16 v[80:83], v[140:143], v[230:233], v[80:83]
	v_mfma_f32_16x16x32_bf16 v[72:75], v[148:151], v[230:233], v[72:75]
	v_mfma_f32_16x16x32_bf16 v[60:63], v[140:143], v[238:241], v[60:63]
	v_mfma_f32_16x16x32_bf16 v[56:59], v[148:151], v[238:241], v[56:59]
	s_setprio 0
	s_setprio 1
	v_mfma_f32_16x16x32_bf16 v[36:39], v[152:155], v[210:213], v[36:39]
	v_mfma_f32_16x16x32_bf16 v[32:35], v[190:193], v[210:213], v[32:35]
	v_mfma_f32_16x16x32_bf16 v[28:31], v[152:155], v[218:221], v[28:31]
	v_mfma_f32_16x16x32_bf16 v[24:27], v[190:193], v[218:221], v[24:27]
	v_mfma_f32_16x16x32_bf16 v[20:23], v[152:155], v[226:229], v[20:23]
	v_mfma_f32_16x16x32_bf16 v[16:19], v[190:193], v[226:229], v[16:19]
	v_mfma_f32_16x16x32_bf16 v[12:15], v[152:155], v[234:237], v[12:15]
	v_mfma_f32_16x16x32_bf16 v[8:11], v[190:193], v[234:237], v[8:11]
	v_mfma_f32_16x16x32_bf16 v[36:39], v[186:189], v[214:217], v[36:39]
	v_mfma_f32_16x16x32_bf16 v[32:35], v[198:201], v[214:217], v[32:35]
	v_mfma_f32_16x16x32_bf16 v[28:31], v[186:189], v[222:225], v[28:31]
	v_mfma_f32_16x16x32_bf16 v[24:27], v[198:201], v[222:225], v[24:27]
	s_barrier
	v_mfma_f32_16x16x32_bf16 v[20:23], v[186:189], v[230:233], v[20:23]
	v_mfma_f32_16x16x32_bf16 v[16:19], v[198:201], v[230:233], v[16:19]
	v_mfma_f32_16x16x32_bf16 v[12:15], v[186:189], v[238:241], v[12:15]
	v_mfma_f32_16x16x32_bf16 v[8:11], v[198:201], v[238:241], v[8:11]
	s_setprio 0
	s_add_i32 s18, 0, 0x18000
	v_add_u32_e32 v0, s18, v194
	ds_read_b128 v[136:139], v0
	ds_read_b128 v[140:143], v0 offset:1024
	ds_read_b128 v[144:147], v0 offset:2048
	ds_read_b128 v[148:151], v0 offset:3072
	v_add_u32_e32 v0, s33, v194
	ds_read_b128 v[152:155], v0
	ds_read_b128 v[186:189], v0 offset:1024
	ds_read_b128 v[190:193], v0 offset:2048
	ds_read_b128 v[198:201], v0 offset:3072
	s_add_u32 s16, s42, 0x40000
	s_addc_u32 s17, s43, 0
	s_mov_b32 m0, s47
	v_lshl_add_u64 v[246:247], s[16:17], 0, v[178:179]
	ds_read_b128 v[210:213], v196 offset:32768
	ds_read_b128 v[214:217], v196 offset:33792
	ds_read_b128 v[218:221], v196 offset:34816
	ds_read_b128 v[222:225], v196 offset:35840
	ds_read_b128 v[226:229], v196 offset:36864
	ds_read_b128 v[230:233], v196 offset:37888
	ds_read_b128 v[234:237], v196 offset:38912
	ds_read_b128 v[238:241], v196 offset:39936
	global_load_lds_dwordx4 v[246:247], off
	v_lshl_add_u64 v[246:247], s[16:17], 0, v[160:161]
	s_mov_b32 m0, s48
	s_nop 0
	global_load_lds_dwordx4 v[246:247], off
	s_waitcnt vmcnt(8)
	s_waitcnt lgkmcnt(0)
	s_barrier
	s_waitcnt lgkmcnt(0)
	v_mfma_f32_16x16x32_bf16 v[132:135], v[136:139], v[210:213], v[132:135]
	v_mfma_f32_16x16x32_bf16 v[128:131], v[144:147], v[210:213], v[128:131]
	v_mfma_f32_16x16x32_bf16 v[124:127], v[136:139], v[218:221], v[124:127]
	v_mfma_f32_16x16x32_bf16 v[120:123], v[144:147], v[218:221], v[120:123]
	s_setprio 1
	v_mfma_f32_16x16x32_bf16 v[116:119], v[136:139], v[226:229], v[116:119]
	v_mfma_f32_16x16x32_bf16 v[112:115], v[144:147], v[226:229], v[112:115]
	v_mfma_f32_16x16x32_bf16 v[108:111], v[136:139], v[234:237], v[108:111]
	v_mfma_f32_16x16x32_bf16 v[104:107], v[144:147], v[234:237], v[104:107]
	v_mfma_f32_16x16x32_bf16 v[132:135], v[140:143], v[214:217], v[132:135]
	v_mfma_f32_16x16x32_bf16 v[128:131], v[148:151], v[214:217], v[128:131]
	v_mfma_f32_16x16x32_bf16 v[124:127], v[140:143], v[222:225], v[124:127]
	v_mfma_f32_16x16x32_bf16 v[120:123], v[148:151], v[222:225], v[120:123]
	v_mfma_f32_16x16x32_bf16 v[116:119], v[140:143], v[230:233], v[116:119]
	v_mfma_f32_16x16x32_bf16 v[112:115], v[148:151], v[230:233], v[112:115]
	v_mfma_f32_16x16x32_bf16 v[108:111], v[140:143], v[238:241], v[108:111]
	v_mfma_f32_16x16x32_bf16 v[104:107], v[148:151], v[238:241], v[104:107]
	s_setprio 0
	s_setprio 1
	v_mfma_f32_16x16x32_bf16 v[84:87], v[152:155], v[210:213], v[84:87]
	v_mfma_f32_16x16x32_bf16 v[76:79], v[190:193], v[210:213], v[76:79]
	v_mfma_f32_16x16x32_bf16 v[68:71], v[152:155], v[218:221], v[68:71]
	v_mfma_f32_16x16x32_bf16 v[64:67], v[190:193], v[218:221], v[64:67]
	v_mfma_f32_16x16x32_bf16 v[52:55], v[152:155], v[226:229], v[52:55]
	v_mfma_f32_16x16x32_bf16 v[48:51], v[190:193], v[226:229], v[48:51]
	v_mfma_f32_16x16x32_bf16 v[44:47], v[152:155], v[234:237], v[44:47]
	v_mfma_f32_16x16x32_bf16 v[40:43], v[190:193], v[234:237], v[40:43]
	v_mfma_f32_16x16x32_bf16 v[84:87], v[186:189], v[214:217], v[84:87]
	v_mfma_f32_16x16x32_bf16 v[76:79], v[198:201], v[214:217], v[76:79]
	v_mfma_f32_16x16x32_bf16 v[68:71], v[186:189], v[222:225], v[68:71]
	v_mfma_f32_16x16x32_bf16 v[64:67], v[198:201], v[222:225], v[64:67]
	s_barrier
; #define PG8_STAGE(bufoff, gbase, voff) do { _Pragma("unroll") for (int _i = 0; _i < 2; ++_i) \
;         __builtin_amdgcn_global_load_lds((const unsigned*)((const char*)(gbase) + (voff)[_i]), (PG8_LAS unsigned*)(lds + (bufoff) + ldsw + _i * 8192), 16, 0, 0); } while (0)
; #define PG8_LDA(dst, b, h) do { _Pragma("unroll") for (int m = 0; m < 4; ++m) _Pragma("unroll") for (int k = 0; k < 2; ++k) dst[m][k] = *(const PG8_LAS bf16x8*)(lds + PG8_SA(b, h) + aoff + m * 2048 + k * 1024); } while (0)
; #define PG8_MMA(ai, bj, At, Bt) do { __builtin_amdgcn_s_setprio(1); _Pragma("unroll") for (int m = 0; m < 4; ++m) _Pragma("unroll") for (int n = 0; n < 2; ++n) _Pragma("unroll") for (int k = 0; k < 2; ++k) \
;         acc[ai][bj][m][n] = __builtin_amdgcn_mfma_f32_16x16x32_bf16(Bt[n][k], At[m][k], acc[ai][bj][m][n], 0, 0, 0); __builtin_amdgcn_s_setprio(0); } while (0)
; #define PG8_WAIT_V(n) asm volatile("s_waitcnt vmcnt(" #n ")" ::: "memory")
; #define PG8_WAIT_L(n) asm volatile("s_waitcnt lgkmcnt(" #n ")" ::: "memory")
; #define PG8_BAR __builtin_amdgcn_s_barrier()
; #define PG8_SCHED __builtin_amdgcn_sched_barrier(0)
; template <class Epi, class Sched, bool ALIGN_EPI = false, bool SP2 = false>
; __device__ __forceinline__ void gemm_phase(PG8_LAS unsigned char* lds, const Gemm g, const Sched& S, const Epi& E) {
;     ...
;             PG8_WAIT_V(8); PG8_WAIT_L(0); PG8_BAR; PG8_MMA(0, 0, At, B0); PG8_MMA(0, 1, At, B1); PG8_BAR; PG8_SCHED;
;             PG8_LDA(At, 1, 1); PG8_STAGE(PG8_SB(1, 0), b3, voffB); PG8_STAGE(PG8_SB(1, 1), b3 + hstep, voffB); PG8_STAGE(PG8_SA(1, 0), a3, voffA);
;             PG8_WAIT_V(8); PG8_WAIT_L(0); PG8_BAR; PG8_MMA(1, 0, At, B0); PG8_MMA(1, 1, At, B1); PG8_BAR; PG8_SCHED;
	v_mfma_f32_16x16x32_bf16 v[52:55], v[186:189], v[230:233], v[52:55]
	v_mfma_f32_16x16x32_bf16 v[48:51], v[198:201], v[230:233], v[48:51]
	v_mfma_f32_16x16x32_bf16 v[44:47], v[186:189], v[238:241], v[44:47]
	v_mfma_f32_16x16x32_bf16 v[40:43], v[198:201], v[238:241], v[40:43]
	s_setprio 0
	s_add_i32 s16, s18, s44
	v_lshl_add_u64 v[2:3], v[2:3], 0, s[20:21]
	s_mov_b32 m0, s16
	ds_read_b128 v[210:213], v196 offset:49152
	ds_read_b128 v[214:217], v196 offset:50176
	ds_read_b128 v[218:221], v196 offset:51200
	ds_read_b128 v[222:225], v196 offset:52224
	ds_read_b128 v[226:229], v196 offset:53248
	ds_read_b128 v[230:233], v196 offset:54272
	ds_read_b128 v[234:237], v196 offset:55296
	ds_read_b128 v[238:241], v196 offset:56320
	global_load_lds_dwordx4 v[2:3], off
	s_add_i32 m0, s16, 0x2000
	s_add_u32 s16, s40, 0x40080
	v_lshl_add_u64 v[2:3], v[156:157], 0, s[20:21]
	s_addc_u32 s17, s41, 0
	s_add_i32 s18, s33, s44
	global_load_lds_dwordx4 v[2:3], off
	v_lshl_add_u64 v[2:3], s[16:17], 0, v[162:163]
	s_mov_b32 m0, s18
	s_nop 0
	global_load_lds_dwordx4 v[2:3], off
	v_lshl_add_u64 v[2:3], s[16:17], 0, v[158:159]
	s_add_i32 m0, s18, 0x2000
	s_nop 0
	global_load_lds_dwordx4 v[2:3], off
	v_lshl_add_u64 v[2:3], v[242:243], 0, s[20:21]
	v_lshl_add_u64 v[244:245], v[244:245], 0, s[20:21]
	s_waitcnt vmcnt(6)
	s_waitcnt lgkmcnt(0)
	s_barrier
	s_waitcnt lgkmcnt(0)
	v_mfma_f32_16x16x32_bf16 v[100:103], v[136:139], v[210:213], v[100:103]
	v_mfma_f32_16x16x32_bf16 v[96:99], v[144:147], v[210:213], v[96:99]
	v_mfma_f32_16x16x32_bf16 v[92:95], v[136:139], v[218:221], v[92:95]
	s_mov_b32 m0, s49
	v_mfma_f32_16x16x32_bf16 v[88:91], v[144:147], v[218:221], v[88:91]
	s_setprio 1
	global_load_lds_dwordx4 v[2:3], off
	v_mfma_f32_16x16x32_bf16 v[80:83], v[136:139], v[226:229], v[80:83]
	v_mfma_f32_16x16x32_bf16 v[72:75], v[144:147], v[226:229], v[72:75]
	v_mfma_f32_16x16x32_bf16 v[60:63], v[136:139], v[234:237], v[60:63]
	v_mfma_f32_16x16x32_bf16 v[56:59], v[144:147], v[234:237], v[56:59]
	v_mfma_f32_16x16x32_bf16 v[100:103], v[140:143], v[214:217], v[100:103]
	v_mfma_f32_16x16x32_bf16 v[96:99], v[148:151], v[214:217], v[96:99]
	v_mfma_f32_16x16x32_bf16 v[92:95], v[140:143], v[222:225], v[92:95]
	s_mov_b32 m0, s50
	v_mfma_f32_16x16x32_bf16 v[88:91], v[148:151], v[222:225], v[88:91]
	global_load_lds_dwordx4 v[244:245], off
	v_mfma_f32_16x16x32_bf16 v[80:83], v[140:143], v[230:233], v[80:83]
	v_mfma_f32_16x16x32_bf16 v[72:75], v[148:151], v[230:233], v[72:75]
	v_mfma_f32_16x16x32_bf16 v[60:63], v[140:143], v[238:241], v[60:63]
	v_mfma_f32_16x16x32_bf16 v[56:59], v[148:151], v[238:241], v[56:59]
	s_setprio 0
	s_setprio 1
	v_mfma_f32_16x16x32_bf16 v[36:39], v[152:155], v[210:213], v[36:39]
	v_mfma_f32_16x16x32_bf16 v[32:35], v[190:193], v[210:213], v[32:35]
	v_mfma_f32_16x16x32_bf16 v[28:31], v[152:155], v[218:221], v[28:31]
	v_mfma_f32_16x16x32_bf16 v[24:27], v[190:193], v[218:221], v[24:27]
	v_mfma_f32_16x16x32_bf16 v[20:23], v[152:155], v[226:229], v[20:23]
	v_mfma_f32_16x16x32_bf16 v[16:19], v[190:193], v[226:229], v[16:19]
	v_mfma_f32_16x16x32_bf16 v[12:15], v[152:155], v[234:237], v[12:15]
	v_mfma_f32_16x16x32_bf16 v[8:11], v[190:193], v[234:237], v[8:11]
	v_mfma_f32_16x16x32_bf16 v[36:39], v[186:189], v[214:217], v[36:39]
	v_mfma_f32_16x16x32_bf16 v[32:35], v[198:201], v[214:217], v[32:35]
	v_mfma_f32_16x16x32_bf16 v[28:31], v[186:189], v[222:225], v[28:31]
	v_mfma_f32_16x16x32_bf16 v[24:27], v[198:201], v[222:225], v[24:27]
	s_barrier
	v_mfma_f32_16x16x32_bf16 v[20:23], v[186:189], v[230:233], v[20:23]
	v_mfma_f32_16x16x32_bf16 v[16:19], v[198:201], v[230:233], v[16:19]
	v_mfma_f32_16x16x32_bf16 v[12:15], v[186:189], v[238:241], v[12:15]
	v_mfma_f32_16x16x32_bf16 v[8:11], v[198:201], v[238:241], v[8:11]
	s_setprio 0
	s_add_i32 s55, s55, 2
	s_add_u32 s8, s8, 0x100
	s_addc_u32 s9, s9, 0
	s_add_u32 s53, s53, 0x100
	s_addc_u32 s54, s54, 0
	s_cmp_gt_u32 s55, 13
	s_cbranch_scc0 .LBB0_165
	s_and_b64 vcc, exec, s[10:11]
	s_cbranch_vccz .LBB0_168
	s_barrier
	s_setprio 1

; #define PG8_STAGE(bufoff, gbase, voff) do { _Pragma("unroll") for (int _i = 0; _i < 2; ++_i) \
;         __builtin_amdgcn_global_load_lds((const unsigned*)((const char*)(gbase) + (voff)[_i]), (PG8_LAS unsigned*)(lds + (bufoff) + ldsw + _i * 8192), 16, 0, 0); } while (0)
; #define PG8_LDA(dst, b, h) do { _Pragma("unroll") for (int m = 0; m < 4; ++m) _Pragma("unroll") for (int k = 0; k < 2; ++k) dst[m][k] = *(const PG8_LAS bf16x8*)(lds + PG8_SA(b, h) + aoff + m * 2048 + k * 1024); } while (0)
; #define PG8_LDB(dst, b, h) do { _Pragma("unroll") for (int n = 0; n < 2; ++n) _Pragma("unroll") for (int k = 0; k < 2; ++k) dst[n][k] = *(const PG8_LAS bf16x8*)(lds + PG8_SB(b, h) + boff + n * 2048 + k * 1024); } while (0)
; #define PG8_MMA(ai, bj, At, Bt) do { __builtin_amdgcn_s_setprio(1); _Pragma("unroll") for (int m = 0; m < 4; ++m) _Pragma("unroll") for (int n = 0; n < 2; ++n) _Pragma("unroll") for (int k = 0; k < 2; ++k) \
;         acc[ai][bj][m][n] = __builtin_amdgcn_mfma_f32_16x16x32_bf16(Bt[n][k], At[m][k], acc[ai][bj][m][n], 0, 0, 0); __builtin_amdgcn_s_setprio(0); } while (0)
; #define PG8_WAIT_V(n) asm volatile("s_waitcnt vmcnt(" #n ")" ::: "memory")
; template <class Epi, class Sched, bool ALIGN_EPI = false, bool SP2 = false>
; __device__ __forceinline__ void gemm_phase(PG8_LAS unsigned char* lds, const Gemm g, const Sched& S, const Epi& E) {
;     ...
;         const char* nA = has_next ? (const char*)g.A + (size_t)nxt.pm * tstep : cA; const char* nB = has_next ? (const char*)g.Bt + (size_t)nxt.pn * tstep : cB;
;         for (int t = 0; t < nt; t += 2) {
;             const bool last = (t == nt - 2);
;             const char* a1 = cA + (size_t)(t + 1) * kstep;
;             const char* a2 = last ? nA : cA + (size_t)(t + 2) * kstep; const char* b2 = last ? nB : cB + (size_t)(t + 2) * kstep;
;             const char* a3 = a2 + kstep; const char* b3 = b2 + kstep;
;             if (last && has_next) S.a_ready(nxt);
;             if constexpr (SP2) {
;             PG8_LDB(B0, 0, 0); PG8_LDB(B1, 0, 1); PG8_SCHED; PG8_LDA(At, 0, 0); PG8_STAGE(PG8_SA(1, 1), a1 + hstep, voffA);
;             PG8_WAIT_V(8); PG8_WAIT_L(0); PG8_BAR; PG8_MMA(0, 0, At, B0); PG8_MMA(0, 1, At, B1); PG8_BAR; PG8_SCHED;
;             PG8_LDA(At, 0, 1); PG8_STAGE(PG8_SB(0, 0), b2, voffB); PG8_STAGE(PG8_SB(0, 1), b2 + hstep, voffB); PG8_STAGE(PG8_SA(0, 0), a2, voffA);
.LBB0_203:
	s_add_i32 s36, s28, 2
	s_add_u32 s16, s24, 0x80
	s_addc_u32 s17, s25, 0
	s_add_i32 s18, 0, 0x10000
	s_cmp_eq_u32 s60, s28
	s_cselect_b32 s29, s3, s17
	s_cselect_b32 s28, s2, s16
	v_add_u32_e32 v137, s18, v200
	s_cselect_b32 s17, s9, s35
	s_cselect_b32 s16, s8, s23
	s_add_i32 s19, 0, 0x14000
	ds_read_b128 v[144:147], v137
	ds_read_b128 v[148:151], v137 offset:1024
	ds_read_b128 v[152:155], v137 offset:2048
	ds_read_b128 v[156:159], v137 offset:3072
	v_add_u32_e32 v137, s19, v200
	ds_read_b128 v[160:163], v137
	ds_read_b128 v[178:181], v137 offset:1024
	ds_read_b128 v[182:185], v137 offset:2048
	ds_read_b128 v[186:189], v137 offset:3072
	v_lshl_add_u64 v[198:199], s[24:25], 0, v[140:141]
	s_add_i32 m0, s52, 0xc000
	ds_read_b128 v[190:193], v210
	ds_read_b128 v[194:197], v210 offset:1024
	ds_read_b128 v[212:215], v210 offset:2048
	ds_read_b128 v[216:219], v210 offset:3072
	ds_read_b128 v[220:223], v210 offset:4096
	ds_read_b128 v[224:227], v210 offset:5120
	ds_read_b128 v[228:231], v210 offset:6144
	ds_read_b128 v[232:235], v210 offset:7168
	global_load_lds_dwordx4 v[198:199], off
	v_lshl_add_u64 v[198:199], s[24:25], 0, v[142:143]
	s_add_i32 m0, s52, 0xe000
	s_nop 0
	global_load_lds_dwordx4 v[198:199], off
	s_waitcnt vmcnt(8)
	s_waitcnt lgkmcnt(0)
	s_barrier
	s_waitcnt lgkmcnt(0)
	v_mfma_f32_16x16x32_bf16 v[132:135], v[144:147], v[190:193], v[132:135]
	v_mfma_f32_16x16x32_bf16 v[128:131], v[152:155], v[190:193], v[128:131]
	v_mfma_f32_16x16x32_bf16 v[116:119], v[144:147], v[212:215], v[116:119]
	v_mfma_f32_16x16x32_bf16 v[112:115], v[152:155], v[212:215], v[112:115]
	s_setprio 1
	v_mfma_f32_16x16x32_bf16 v[100:103], v[144:147], v[220:223], v[100:103]
	v_mfma_f32_16x16x32_bf16 v[96:99], v[152:155], v[220:223], v[96:99]
	v_mfma_f32_16x16x32_bf16 v[84:87], v[144:147], v[228:231], v[84:87]
	v_mfma_f32_16x16x32_bf16 v[80:83], v[152:155], v[228:231], v[80:83]
	v_mfma_f32_16x16x32_bf16 v[132:135], v[148:151], v[194:197], v[132:135]
	v_mfma_f32_16x16x32_bf16 v[128:131], v[156:159], v[194:197], v[128:131]
	v_mfma_f32_16x16x32_bf16 v[116:119], v[148:151], v[216:219], v[116:119]
	v_mfma_f32_16x16x32_bf16 v[112:115], v[156:159], v[216:219], v[112:115]
	v_mfma_f32_16x16x32_bf16 v[100:103], v[148:151], v[224:227], v[100:103]
	v_mfma_f32_16x16x32_bf16 v[96:99], v[156:159], v[224:227], v[96:99]
	v_mfma_f32_16x16x32_bf16 v[84:87], v[148:151], v[232:235], v[84:87]
	v_mfma_f32_16x16x32_bf16 v[80:83], v[156:159], v[232:235], v[80:83]
	s_setprio 0
	s_setprio 1
	v_mfma_f32_16x16x32_bf16 v[124:127], v[160:163], v[190:193], v[124:127]
	v_mfma_f32_16x16x32_bf16 v[120:123], v[182:185], v[190:193], v[120:123]
	v_mfma_f32_16x16x32_bf16 v[108:111], v[160:163], v[212:215], v[108:111]
	v_mfma_f32_16x16x32_bf16 v[104:107], v[182:185], v[212:215], v[104:107]
	v_mfma_f32_16x16x32_bf16 v[92:95], v[160:163], v[220:223], v[92:95]
	v_mfma_f32_16x16x32_bf16 v[88:91], v[182:185], v[220:223], v[88:91]
	v_mfma_f32_16x16x32_bf16 v[76:79], v[160:163], v[228:231], v[76:79]
	v_mfma_f32_16x16x32_bf16 v[72:75], v[182:185], v[228:231], v[72:75]
	v_mfma_f32_16x16x32_bf16 v[124:127], v[178:181], v[194:197], v[124:127]
	v_mfma_f32_16x16x32_bf16 v[120:123], v[186:189], v[194:197], v[120:123]
	v_mfma_f32_16x16x32_bf16 v[108:111], v[178:181], v[216:219], v[108:111]
	v_mfma_f32_16x16x32_bf16 v[104:107], v[186:189], v[216:219], v[104:107]
	s_barrier
	v_mfma_f32_16x16x32_bf16 v[92:95], v[178:181], v[224:227], v[92:95]
	v_mfma_f32_16x16x32_bf16 v[88:91], v[186:189], v[224:227], v[88:91]
	v_mfma_f32_16x16x32_bf16 v[76:79], v[178:181], v[232:235], v[76:79]
	v_mfma_f32_16x16x32_bf16 v[72:75], v[186:189], v[232:235], v[72:75]
	s_setprio 0
	s_add_i32 s18, s18, s41
	v_lshl_add_u64 v[198:199], s[16:17], 0, v[0:1]
	s_mov_b32 m0, s18
	ds_read_b128 v[190:193], v210 offset:16384
	ds_read_b128 v[194:197], v210 offset:17408
	ds_read_b128 v[212:215], v210 offset:18432
	ds_read_b128 v[216:219], v210 offset:19456
	ds_read_b128 v[220:223], v210 offset:20480
	ds_read_b128 v[224:227], v210 offset:21504
	ds_read_b128 v[228:231], v210 offset:22528
	ds_read_b128 v[232:235], v210 offset:23552
	global_load_lds_dwordx4 v[198:199], off
	s_add_i32 m0, s18, 0x2000
	v_lshl_add_u64 v[236:237], s[16:17], 0, v[2:3]
	s_add_u32 s16, s16, s12
	s_addc_u32 s17, s17, 0
	s_add_i32 s18, s19, s41
	global_load_lds_dwordx4 v[236:237], off
	v_lshl_add_u64 v[238:239], s[16:17], 0, v[0:1]
	s_mov_b32 m0, s18
	v_lshl_add_u64 v[240:241], s[16:17], 0, v[2:3]
	global_load_lds_dwordx4 v[238:239], off
	s_add_i32 m0, s18, 0x2000
	v_lshl_add_u64 v[242:243], s[28:29], 0, v[0:1]
	global_load_lds_dwordx4 v[240:241], off
	v_lshl_add_u64 v[244:245], s[28:29], 0, v[2:3]
	s_waitcnt vmcnt(6)
	s_waitcnt lgkmcnt(0)
	s_barrier
; #define PG8_STAGE(bufoff, gbase, voff) do { _Pragma("unroll") for (int _i = 0; _i < 2; ++_i) \
;         __builtin_amdgcn_global_load_lds((const unsigned*)((const char*)(gbase) + (voff)[_i]), (PG8_LAS unsigned*)(lds + (bufoff) + ldsw + _i * 8192), 16, 0, 0); } while (0)
; #define PG8_LDA(dst, b, h) do { _Pragma("unroll") for (int m = 0; m < 4; ++m) _Pragma("unroll") for (int k = 0; k < 2; ++k) dst[m][k] = *(const PG8_LAS bf16x8*)(lds + PG8_SA(b, h) + aoff + m * 2048 + k * 1024); } while (0)
; #define PG8_LDB(dst, b, h) do { _Pragma("unroll") for (int n = 0; n < 2; ++n) _Pragma("unroll") for (int k = 0; k < 2; ++k) dst[n][k] = *(const PG8_LAS bf16x8*)(lds + PG8_SB(b, h) + boff + n * 2048 + k * 1024); } while (0)
; #define PG8_MMA(ai, bj, At, Bt) do { __builtin_amdgcn_s_setprio(1); _Pragma("unroll") for (int m = 0; m < 4; ++m) _Pragma("unroll") for (int n = 0; n < 2; ++n) _Pragma("unroll") for (int k = 0; k < 2; ++k) \
;         acc[ai][bj][m][n] = __builtin_amdgcn_mfma_f32_16x16x32_bf16(Bt[n][k], At[m][k], acc[ai][bj][m][n], 0, 0, 0); __builtin_amdgcn_s_setprio(0); } while (0)
; #define PG8_WAIT_V(n) asm volatile("s_waitcnt vmcnt(" #n ")" ::: "memory")
; #define PG8_WAIT_L(n) asm volatile("s_waitcnt lgkmcnt(" #n ")" ::: "memory")
; #define PG8_BAR __builtin_amdgcn_s_barrier()
; #define PG8_SCHED __builtin_amdgcn_sched_barrier(0)
; template <class Epi, class Sched, bool ALIGN_EPI = false, bool SP2 = false>
; __device__ __forceinline__ void gemm_phase(PG8_LAS unsigned char* lds, const Gemm g, const Sched& S, const Epi& E) {
;     ...
;             PG8_WAIT_V(8); PG8_WAIT_L(0); PG8_BAR; PG8_MMA(1, 0, At, B0); PG8_MMA(1, 1, At, B1); PG8_BAR; PG8_SCHED;
;             PG8_LDB(B0, 1, 0); PG8_LDB(B1, 1, 1); PG8_SCHED; PG8_LDA(At, 1, 0); PG8_STAGE(PG8_SA(0, 1), a2 + hstep, voffA);
;             PG8_WAIT_V(8); PG8_WAIT_L(0); PG8_BAR; PG8_MMA(0, 0, At, B0); PG8_MMA(0, 1, At, B1); PG8_BAR; PG8_SCHED;
	s_waitcnt lgkmcnt(0)
	v_mfma_f32_16x16x32_bf16 v[68:71], v[144:147], v[190:193], v[68:71]
	v_mfma_f32_16x16x32_bf16 v[64:67], v[152:155], v[190:193], v[64:67]
	v_mfma_f32_16x16x32_bf16 v[52:55], v[144:147], v[212:215], v[52:55]
	s_mov_b32 m0, s52
	v_mfma_f32_16x16x32_bf16 v[48:51], v[152:155], v[212:215], v[48:51]
	s_setprio 1
	global_load_lds_dwordx4 v[242:243], off
	v_mfma_f32_16x16x32_bf16 v[36:39], v[144:147], v[220:223], v[36:39]
	v_mfma_f32_16x16x32_bf16 v[32:35], v[152:155], v[220:223], v[32:35]
	v_mfma_f32_16x16x32_bf16 v[20:23], v[144:147], v[228:231], v[20:23]
	v_mfma_f32_16x16x32_bf16 v[16:19], v[152:155], v[228:231], v[16:19]
	v_mfma_f32_16x16x32_bf16 v[68:71], v[148:151], v[194:197], v[68:71]
	v_mfma_f32_16x16x32_bf16 v[64:67], v[156:159], v[194:197], v[64:67]
	v_mfma_f32_16x16x32_bf16 v[52:55], v[148:151], v[216:219], v[52:55]
	s_mov_b32 m0, s53
	v_mfma_f32_16x16x32_bf16 v[48:51], v[156:159], v[216:219], v[48:51]
	global_load_lds_dwordx4 v[244:245], off
	v_mfma_f32_16x16x32_bf16 v[36:39], v[148:151], v[224:227], v[36:39]
	v_mfma_f32_16x16x32_bf16 v[32:35], v[156:159], v[224:227], v[32:35]
	v_mfma_f32_16x16x32_bf16 v[20:23], v[148:151], v[232:235], v[20:23]
	v_mfma_f32_16x16x32_bf16 v[16:19], v[156:159], v[232:235], v[16:19]
	s_setprio 0
	s_setprio 1
	v_mfma_f32_16x16x32_bf16 v[60:63], v[160:163], v[190:193], v[60:63]
	v_mfma_f32_16x16x32_bf16 v[56:59], v[182:185], v[190:193], v[56:59]
	v_mfma_f32_16x16x32_bf16 v[44:47], v[160:163], v[212:215], v[44:47]
	v_mfma_f32_16x16x32_bf16 v[40:43], v[182:185], v[212:215], v[40:43]
	v_mfma_f32_16x16x32_bf16 v[28:31], v[160:163], v[220:223], v[28:31]
	v_mfma_f32_16x16x32_bf16 v[24:27], v[182:185], v[220:223], v[24:27]
	v_mfma_f32_16x16x32_bf16 v[12:15], v[160:163], v[228:231], v[12:15]
	v_mfma_f32_16x16x32_bf16 v[8:11], v[182:185], v[228:231], v[8:11]
	v_mfma_f32_16x16x32_bf16 v[60:63], v[178:181], v[194:197], v[60:63]
	v_mfma_f32_16x16x32_bf16 v[56:59], v[186:189], v[194:197], v[56:59]
	v_mfma_f32_16x16x32_bf16 v[44:47], v[178:181], v[216:219], v[44:47]
	v_mfma_f32_16x16x32_bf16 v[40:43], v[186:189], v[216:219], v[40:43]
	s_barrier
	v_mfma_f32_16x16x32_bf16 v[28:31], v[178:181], v[224:227], v[28:31]
	v_mfma_f32_16x16x32_bf16 v[24:27], v[186:189], v[224:227], v[24:27]
	v_mfma_f32_16x16x32_bf16 v[12:15], v[178:181], v[232:235], v[12:15]
	v_mfma_f32_16x16x32_bf16 v[8:11], v[186:189], v[232:235], v[8:11]
	s_setprio 0
	s_add_i32 s18, 0, 0x18000
	v_add_u32_e32 v137, s18, v200
	ds_read_b128 v[144:147], v137
	ds_read_b128 v[148:151], v137 offset:1024
	ds_read_b128 v[152:155], v137 offset:2048
	ds_read_b128 v[156:159], v137 offset:3072
	v_add_u32_e32 v137, s33, v200
	ds_read_b128 v[160:163], v137
	ds_read_b128 v[178:181], v137 offset:1024
	ds_read_b128 v[182:185], v137 offset:2048
	ds_read_b128 v[186:189], v137 offset:3072
	s_add_u32 s16, s28, s12
	s_addc_u32 s17, s29, 0
	s_mov_b32 m0, s54
	v_lshl_add_u64 v[246:247], s[16:17], 0, v[0:1]
	ds_read_b128 v[190:193], v210 offset:32768
	ds_read_b128 v[194:197], v210 offset:33792
	ds_read_b128 v[212:215], v210 offset:34816
	ds_read_b128 v[216:219], v210 offset:35840
	ds_read_b128 v[220:223], v210 offset:36864
	ds_read_b128 v[224:227], v210 offset:37888
	ds_read_b128 v[228:231], v210 offset:38912
	ds_read_b128 v[232:235], v210 offset:39936
	global_load_lds_dwordx4 v[246:247], off
	v_lshl_add_u64 v[246:247], s[16:17], 0, v[2:3]
	s_mov_b32 m0, s55
	s_nop 0
	global_load_lds_dwordx4 v[246:247], off
	s_waitcnt vmcnt(8)
	s_waitcnt lgkmcnt(0)
	s_barrier
	s_waitcnt lgkmcnt(0)
	v_mfma_f32_16x16x32_bf16 v[132:135], v[144:147], v[190:193], v[132:135]
	v_mfma_f32_16x16x32_bf16 v[128:131], v[152:155], v[190:193], v[128:131]
	v_mfma_f32_16x16x32_bf16 v[116:119], v[144:147], v[212:215], v[116:119]
	v_mfma_f32_16x16x32_bf16 v[112:115], v[152:155], v[212:215], v[112:115]
	s_setprio 1
	v_mfma_f32_16x16x32_bf16 v[100:103], v[144:147], v[220:223], v[100:103]
	v_mfma_f32_16x16x32_bf16 v[96:99], v[152:155], v[220:223], v[96:99]
	v_mfma_f32_16x16x32_bf16 v[84:87], v[144:147], v[228:231], v[84:87]
	v_mfma_f32_16x16x32_bf16 v[80:83], v[152:155], v[228:231], v[80:83]
	v_mfma_f32_16x16x32_bf16 v[132:135], v[148:151], v[194:197], v[132:135]
	v_mfma_f32_16x16x32_bf16 v[128:131], v[156:159], v[194:197], v[128:131]
	v_mfma_f32_16x16x32_bf16 v[116:119], v[148:151], v[216:219], v[116:119]
	v_mfma_f32_16x16x32_bf16 v[112:115], v[156:159], v[216:219], v[112:115]
	v_mfma_f32_16x16x32_bf16 v[100:103], v[148:151], v[224:227], v[100:103]
	v_mfma_f32_16x16x32_bf16 v[96:99], v[156:159], v[224:227], v[96:99]
	v_mfma_f32_16x16x32_bf16 v[84:87], v[148:151], v[232:235], v[84:87]
	v_mfma_f32_16x16x32_bf16 v[80:83], v[156:159], v[232:235], v[80:83]
	s_setprio 0
	s_setprio 1
	v_mfma_f32_16x16x32_bf16 v[124:127], v[160:163], v[190:193], v[124:127]
	v_mfma_f32_16x16x32_bf16 v[120:123], v[182:185], v[190:193], v[120:123]
	v_mfma_f32_16x16x32_bf16 v[108:111], v[160:163], v[212:215], v[108:111]
	v_mfma_f32_16x16x32_bf16 v[104:107], v[182:185], v[212:215], v[104:107]
	v_mfma_f32_16x16x32_bf16 v[92:95], v[160:163], v[220:223], v[92:95]
	v_mfma_f32_16x16x32_bf16 v[88:91], v[182:185], v[220:223], v[88:91]
	v_mfma_f32_16x16x32_bf16 v[76:79], v[160:163], v[228:231], v[76:79]
	v_mfma_f32_16x16x32_bf16 v[72:75], v[182:185], v[228:231], v[72:75]
	v_mfma_f32_16x16x32_bf16 v[124:127], v[178:181], v[194:197], v[124:127]
	v_mfma_f32_16x16x32_bf16 v[120:123], v[186:189], v[194:197], v[120:123]
	v_mfma_f32_16x16x32_bf16 v[108:111], v[178:181], v[216:219], v[108:111]
	v_mfma_f32_16x16x32_bf16 v[104:107], v[186:189], v[216:219], v[104:107]
	s_barrier
; #define PG8_STAGE(bufoff, gbase, voff) do { _Pragma("unroll") for (int _i = 0; _i < 2; ++_i) \
;         __builtin_amdgcn_global_load_lds((const unsigned*)((const char*)(gbase) + (voff)[_i]), (PG8_LAS unsigned*)(lds + (bufoff) + ldsw + _i * 8192), 16, 0, 0); } while (0)
; #define PG8_LDA(dst, b, h) do { _Pragma("unroll") for (int m = 0; m < 4; ++m) _Pragma("unroll") for (int k = 0; k < 2; ++k) dst[m][k] = *(const PG8_LAS bf16x8*)(lds + PG8_SA(b, h) + aoff + m * 2048 + k * 1024); } while (0)
; #define PG8_MMA(ai, bj, At, Bt) do { __builtin_amdgcn_s_setprio(1); _Pragma("unroll") for (int m = 0; m < 4; ++m) _Pragma("unroll") for (int n = 0; n < 2; ++n) _Pragma("unroll") for (int k = 0; k < 2; ++k) \
;         acc[ai][bj][m][n] = __builtin_amdgcn_mfma_f32_16x16x32_bf16(Bt[n][k], At[m][k], acc[ai][bj][m][n], 0, 0, 0); __builtin_amdgcn_s_setprio(0); } while (0)
; #define PG8_WAIT_V(n) asm volatile("s_waitcnt vmcnt(" #n ")" ::: "memory")
; #define PG8_WAIT_L(n) asm volatile("s_waitcnt lgkmcnt(" #n ")" ::: "memory")
; #define PG8_BAR __builtin_amdgcn_s_barrier()
; #define PG8_SCHED __builtin_amdgcn_sched_barrier(0)
; template <class Epi, class Sched, bool ALIGN_EPI = false, bool SP2 = false>
; __device__ __forceinline__ void gemm_phase(PG8_LAS unsigned char* lds, const Gemm g, const Sched& S, const Epi& E) {
;     ...
;             PG8_WAIT_V(8); PG8_WAIT_L(0); PG8_BAR; PG8_MMA(0, 0, At, B0); PG8_MMA(0, 1, At, B1); PG8_BAR; PG8_SCHED;
;             PG8_LDA(At, 1, 1); PG8_STAGE(PG8_SB(1, 0), b3, voffB); PG8_STAGE(PG8_SB(1, 1), b3 + hstep, voffB); PG8_STAGE(PG8_SA(1, 0), a3, voffA);
;             PG8_WAIT_V(8); PG8_WAIT_L(0); PG8_BAR; PG8_MMA(1, 0, At, B0); PG8_MMA(1, 1, At, B1); PG8_BAR; PG8_SCHED;
	v_mfma_f32_16x16x32_bf16 v[92:95], v[178:181], v[224:227], v[92:95]
	v_mfma_f32_16x16x32_bf16 v[88:91], v[186:189], v[224:227], v[88:91]
	v_mfma_f32_16x16x32_bf16 v[76:79], v[178:181], v[232:235], v[76:79]
	v_mfma_f32_16x16x32_bf16 v[72:75], v[186:189], v[232:235], v[72:75]
	s_setprio 0
	s_add_i32 s16, s18, s41
	v_lshl_add_u64 v[198:199], v[198:199], 0, s[20:21]
	s_mov_b32 m0, s16
	ds_read_b128 v[190:193], v210 offset:49152
	ds_read_b128 v[194:197], v210 offset:50176
	ds_read_b128 v[212:215], v210 offset:51200
	ds_read_b128 v[216:219], v210 offset:52224
	ds_read_b128 v[220:223], v210 offset:53248
	ds_read_b128 v[224:227], v210 offset:54272
	ds_read_b128 v[228:231], v210 offset:55296
	ds_read_b128 v[232:235], v210 offset:56320
	global_load_lds_dwordx4 v[198:199], off
	v_lshl_add_u64 v[198:199], v[236:237], 0, s[20:21]
	s_add_i32 m0, s16, 0x2000
	s_add_i32 s16, s33, s41
	global_load_lds_dwordx4 v[198:199], off
	v_lshl_add_u64 v[198:199], v[238:239], 0, s[20:21]
	s_mov_b32 m0, s16
	s_nop 0
	global_load_lds_dwordx4 v[198:199], off
	v_lshl_add_u64 v[198:199], v[240:241], 0, s[20:21]
	s_add_i32 m0, s16, 0x2000
	s_nop 0
	global_load_lds_dwordx4 v[198:199], off
	v_lshl_add_u64 v[198:199], v[242:243], 0, s[20:21]
	v_lshl_add_u64 v[244:245], v[244:245], 0, s[20:21]
	s_waitcnt vmcnt(6)
	s_waitcnt lgkmcnt(0)
	s_barrier
	s_waitcnt lgkmcnt(0)
	v_mfma_f32_16x16x32_bf16 v[68:71], v[144:147], v[190:193], v[68:71]
	v_mfma_f32_16x16x32_bf16 v[64:67], v[152:155], v[190:193], v[64:67]
	v_mfma_f32_16x16x32_bf16 v[52:55], v[144:147], v[212:215], v[52:55]
	s_mov_b32 m0, s56
	v_mfma_f32_16x16x32_bf16 v[48:51], v[152:155], v[212:215], v[48:51]
	s_setprio 1
	global_load_lds_dwordx4 v[198:199], off
	v_mfma_f32_16x16x32_bf16 v[36:39], v[144:147], v[220:223], v[36:39]
	v_mfma_f32_16x16x32_bf16 v[32:35], v[152:155], v[220:223], v[32:35]
	v_mfma_f32_16x16x32_bf16 v[20:23], v[144:147], v[228:231], v[20:23]
	v_mfma_f32_16x16x32_bf16 v[16:19], v[152:155], v[228:231], v[16:19]
	v_mfma_f32_16x16x32_bf16 v[68:71], v[148:151], v[194:197], v[68:71]
	v_mfma_f32_16x16x32_bf16 v[64:67], v[156:159], v[194:197], v[64:67]
	v_mfma_f32_16x16x32_bf16 v[52:55], v[148:151], v[216:219], v[52:55]
	s_mov_b32 m0, s57
	v_mfma_f32_16x16x32_bf16 v[48:51], v[156:159], v[216:219], v[48:51]
	global_load_lds_dwordx4 v[244:245], off
	v_mfma_f32_16x16x32_bf16 v[36:39], v[148:151], v[224:227], v[36:39]
	v_mfma_f32_16x16x32_bf16 v[32:35], v[156:159], v[224:227], v[32:35]
	v_mfma_f32_16x16x32_bf16 v[20:23], v[148:151], v[232:235], v[20:23]
	v_mfma_f32_16x16x32_bf16 v[16:19], v[156:159], v[232:235], v[16:19]
	s_setprio 0
	s_setprio 1
	v_mfma_f32_16x16x32_bf16 v[60:63], v[160:163], v[190:193], v[60:63]
	v_mfma_f32_16x16x32_bf16 v[56:59], v[182:185], v[190:193], v[56:59]
	v_mfma_f32_16x16x32_bf16 v[44:47], v[160:163], v[212:215], v[44:47]
	v_mfma_f32_16x16x32_bf16 v[40:43], v[182:185], v[212:215], v[40:43]
	v_mfma_f32_16x16x32_bf16 v[28:31], v[160:163], v[220:223], v[28:31]
	v_mfma_f32_16x16x32_bf16 v[24:27], v[182:185], v[220:223], v[24:27]
	v_mfma_f32_16x16x32_bf16 v[12:15], v[160:163], v[228:231], v[12:15]
	v_mfma_f32_16x16x32_bf16 v[8:11], v[182:185], v[228:231], v[8:11]
	v_mfma_f32_16x16x32_bf16 v[60:63], v[178:181], v[194:197], v[60:63]
	v_mfma_f32_16x16x32_bf16 v[56:59], v[186:189], v[194:197], v[56:59]
	v_mfma_f32_16x16x32_bf16 v[44:47], v[178:181], v[216:219], v[44:47]
	v_mfma_f32_16x16x32_bf16 v[40:43], v[186:189], v[216:219], v[40:43]
	s_barrier
	v_mfma_f32_16x16x32_bf16 v[28:31], v[178:181], v[224:227], v[28:31]
	v_mfma_f32_16x16x32_bf16 v[24:27], v[186:189], v[224:227], v[24:27]
	v_mfma_f32_16x16x32_bf16 v[12:15], v[178:181], v[232:235], v[12:15]
	v_mfma_f32_16x16x32_bf16 v[8:11], v[186:189], v[232:235], v[8:11]
	s_setprio 0
	s_add_u32 s24, s24, 0x100
	s_addc_u32 s25, s25, 0
	s_add_u32 s23, s23, 0x100
	s_addc_u32 s35, s35, 0
	s_cmp_ge_u32 s36, s59
	s_mov_b32 s28, s36
	s_cbranch_scc0 .LBB0_203
	s_and_b64 vcc, exec, s[46:47]
	s_cbranch_vccz .LBB0_206
	s_barrier
	s_setprio 1

; #define PG8_STAGE(bufoff, gbase, voff) do { _Pragma("unroll") for (int _i = 0; _i < 2; ++_i) \
;         __builtin_amdgcn_global_load_lds((const unsigned*)((const char*)(gbase) + (voff)[_i]), (PG8_LAS unsigned*)(lds + (bufoff) + ldsw + _i * 8192), 16, 0, 0); } while (0)
; #define PG8_LDA(dst, b, h) do { _Pragma("unroll") for (int m = 0; m < 4; ++m) _Pragma("unroll") for (int k = 0; k < 2; ++k) dst[m][k] = *(const PG8_LAS bf16x8*)(lds + PG8_SA(b, h) + aoff + m * 2048 + k * 1024); } while (0)
; #define PG8_LDB(dst, b, h) do { _Pragma("unroll") for (int n = 0; n < 2; ++n) _Pragma("unroll") for (int k = 0; k < 2; ++k) dst[n][k] = *(const PG8_LAS bf16x8*)(lds + PG8_SB(b, h) + boff + n * 2048 + k * 1024); } while (0)
; #define PG8_MMA(ai, bj, At, Bt) do { __builtin_amdgcn_s_setprio(1); _Pragma("unroll") for (int m = 0; m < 4; ++m) _Pragma("unroll") for (int n = 0; n < 2; ++n) _Pragma("unroll") for (int k = 0; k < 2; ++k) \
;         acc[ai][bj][m][n] = __builtin_amdgcn_mfma_f32_16x16x32_bf16(Bt[n][k], At[m][k], acc[ai][bj][m][n], 0, 0, 0); __builtin_amdgcn_s_setprio(0); } while (0)
; #define PG8_WAIT_V(n) asm volatile("s_waitcnt vmcnt(" #n ")" ::: "memory")
; #define PG8_WAIT_L(n) asm volatile("s_waitcnt lgkmcnt(" #n ")" ::: "memory")
; #define PG8_BAR __builtin_amdgcn_s_barrier()
; #define PG8_SCHED __builtin_amdgcn_sched_barrier(0)
; template <class Epi, class Sched, bool ALIGN_EPI = false, bool SP2 = false>
; __device__ __forceinline__ void gemm_phase(PG8_LAS unsigned char* lds, const Gemm g, const Sched& S, const Epi& E) {
;     ...
;             const bool last = (t == nt - 2);
;             const char* a1 = cA + (size_t)(t + 1) * kstep;
;             const char* a2 = last ? nA : cA + (size_t)(t + 2) * kstep; const char* b2 = last ? nB : cB + (size_t)(t + 2) * kstep;
;             const char* a3 = a2 + kstep; const char* b3 = b2 + kstep;
;             if (last && has_next) S.a_ready(nxt);
;             if constexpr (SP2) {
;             PG8_LDB(B0, 0, 0); PG8_LDB(B1, 0, 1); PG8_SCHED; PG8_LDA(At, 0, 0); PG8_STAGE(PG8_SA(1, 1), a1 + hstep, voffA);
;             PG8_WAIT_V(8); PG8_WAIT_L(0); PG8_BAR; PG8_MMA(0, 0, At, B0); PG8_MMA(0, 1, At, B1); PG8_BAR; PG8_SCHED;
;             PG8_LDA(At, 0, 1); PG8_STAGE(PG8_SB(0, 0), b2, voffB); PG8_STAGE(PG8_SB(0, 1), b2 + hstep, voffB); PG8_STAGE(PG8_SA(0, 0), a2, voffA);
.LBB0_257:
	s_add_u32 s16, s8, 0xfffc0080
	s_addc_u32 s17, s9, -1
	s_add_i32 s18, 0, 0x10000
	s_cmp_eq_u32 s55, 12
	s_cselect_b32 s43, s14, s17
	s_cselect_b32 s42, s15, s16
	v_add_u32_e32 v0, s18, v210
	s_cselect_b32 s41, s13, s54
	s_cselect_b32 s40, s25, s53
	s_add_i32 s19, 0, 0x14000
	ds_read_b128 v[104:107], v0
	ds_read_b128 v[140:143], v0 offset:1024
	ds_read_b128 v[144:147], v0 offset:2048
	ds_read_b128 v[148:151], v0 offset:3072
	v_add_u32_e32 v0, s19, v210
	ds_read_b128 v[152:155], v0
	ds_read_b128 v[156:159], v0 offset:1024
	ds_read_b128 v[160:163], v0 offset:2048
	ds_read_b128 v[192:195], v0 offset:3072
	v_lshl_add_u64 v[2:3], s[8:9], 0, v[188:189]
	s_add_i32 m0, s44, 0xc000
	ds_read_b128 v[196:199], v212
	ds_read_b128 v[214:217], v212 offset:1024
	ds_read_b128 v[218:221], v212 offset:2048
	ds_read_b128 v[222:225], v212 offset:3072
	ds_read_b128 v[226:229], v212 offset:4096
	ds_read_b128 v[230:233], v212 offset:5120
	ds_read_b128 v[234:237], v212 offset:6144
	ds_read_b128 v[238:241], v212 offset:7168
	global_load_lds_dwordx4 v[2:3], off
	v_lshl_add_u64 v[2:3], s[8:9], 0, v[190:191]
	s_add_i32 m0, s44, 0xe000
	s_nop 0
	global_load_lds_dwordx4 v[2:3], off
	s_waitcnt vmcnt(8)
	s_waitcnt lgkmcnt(0)
	s_barrier
	s_waitcnt lgkmcnt(0)
	v_mfma_f32_16x16x32_bf16 v[136:139], v[104:107], v[196:199], v[136:139]
	v_mfma_f32_16x16x32_bf16 v[128:131], v[144:147], v[196:199], v[128:131]
	v_mfma_f32_16x16x32_bf16 v[120:123], v[104:107], v[218:221], v[120:123]
	v_mfma_f32_16x16x32_bf16 v[112:115], v[144:147], v[218:221], v[112:115]
	s_setprio 1
	v_mfma_f32_16x16x32_bf16 v[100:103], v[104:107], v[226:229], v[100:103]
	v_mfma_f32_16x16x32_bf16 v[92:95], v[144:147], v[226:229], v[92:95]
	v_mfma_f32_16x16x32_bf16 v[84:87], v[104:107], v[234:237], v[84:87]
	v_mfma_f32_16x16x32_bf16 v[76:79], v[144:147], v[234:237], v[76:79]
	v_mfma_f32_16x16x32_bf16 v[136:139], v[140:143], v[214:217], v[136:139]
	v_mfma_f32_16x16x32_bf16 v[128:131], v[148:151], v[214:217], v[128:131]
	v_mfma_f32_16x16x32_bf16 v[120:123], v[140:143], v[222:225], v[120:123]
	v_mfma_f32_16x16x32_bf16 v[112:115], v[148:151], v[222:225], v[112:115]
	v_mfma_f32_16x16x32_bf16 v[100:103], v[140:143], v[230:233], v[100:103]
	v_mfma_f32_16x16x32_bf16 v[92:95], v[148:151], v[230:233], v[92:95]
	v_mfma_f32_16x16x32_bf16 v[84:87], v[140:143], v[238:241], v[84:87]
	v_mfma_f32_16x16x32_bf16 v[76:79], v[148:151], v[238:241], v[76:79]
	s_setprio 0
	s_setprio 1
	v_mfma_f32_16x16x32_bf16 v[132:135], v[152:155], v[196:199], v[132:135]
	v_mfma_f32_16x16x32_bf16 v[124:127], v[160:163], v[196:199], v[124:127]
	v_mfma_f32_16x16x32_bf16 v[116:119], v[152:155], v[218:221], v[116:119]
	v_mfma_f32_16x16x32_bf16 v[108:111], v[160:163], v[218:221], v[108:111]
	v_mfma_f32_16x16x32_bf16 v[96:99], v[152:155], v[226:229], v[96:99]
	v_mfma_f32_16x16x32_bf16 v[88:91], v[160:163], v[226:229], v[88:91]
	v_mfma_f32_16x16x32_bf16 v[80:83], v[152:155], v[234:237], v[80:83]
	v_mfma_f32_16x16x32_bf16 v[72:75], v[160:163], v[234:237], v[72:75]
	v_mfma_f32_16x16x32_bf16 v[132:135], v[156:159], v[214:217], v[132:135]
	v_mfma_f32_16x16x32_bf16 v[124:127], v[192:195], v[214:217], v[124:127]
	v_mfma_f32_16x16x32_bf16 v[116:119], v[156:159], v[222:225], v[116:119]
	v_mfma_f32_16x16x32_bf16 v[108:111], v[192:195], v[222:225], v[108:111]
	s_barrier
	v_mfma_f32_16x16x32_bf16 v[96:99], v[156:159], v[230:233], v[96:99]
	v_mfma_f32_16x16x32_bf16 v[88:91], v[192:195], v[230:233], v[88:91]
	v_mfma_f32_16x16x32_bf16 v[80:83], v[156:159], v[238:241], v[80:83]
	v_mfma_f32_16x16x32_bf16 v[72:75], v[192:195], v[238:241], v[72:75]
	s_setprio 0
	s_add_i32 s16, s18, s36
	v_lshl_add_u64 v[2:3], s[40:41], 0, v[182:183]
	s_mov_b32 m0, s16
	ds_read_b128 v[196:199], v212 offset:16384
	ds_read_b128 v[214:217], v212 offset:17408
	ds_read_b128 v[218:221], v212 offset:18432
	ds_read_b128 v[222:225], v212 offset:19456
	ds_read_b128 v[226:229], v212 offset:20480
	ds_read_b128 v[230:233], v212 offset:21504
	ds_read_b128 v[234:237], v212 offset:22528
	ds_read_b128 v[238:241], v212 offset:23552
	global_load_lds_dwordx4 v[2:3], off
	s_add_i32 m0, s16, 0x2000
	s_add_u32 s16, s40, 0x40000
	v_lshl_add_u64 v[200:201], s[40:41], 0, v[178:179]
	s_addc_u32 s17, s41, 0
	s_add_i32 s18, s19, s36
	global_load_lds_dwordx4 v[200:201], off
	v_lshl_add_u64 v[242:243], s[16:17], 0, v[182:183]
	s_mov_b32 m0, s18
	v_lshl_add_u64 v[244:245], s[42:43], 0, v[180:181]
	global_load_lds_dwordx4 v[242:243], off
	v_lshl_add_u64 v[242:243], s[16:17], 0, v[178:179]
	s_add_i32 m0, s18, 0x2000
	s_nop 0
	global_load_lds_dwordx4 v[242:243], off
	v_lshl_add_u64 v[242:243], s[42:43], 0, v[184:185]
	s_waitcnt vmcnt(6)
	s_waitcnt lgkmcnt(0)
	s_barrier
; #define PG8_STAGE(bufoff, gbase, voff) do { _Pragma("unroll") for (int _i = 0; _i < 2; ++_i) \
;         __builtin_amdgcn_global_load_lds((const unsigned*)((const char*)(gbase) + (voff)[_i]), (PG8_LAS unsigned*)(lds + (bufoff) + ldsw + _i * 8192), 16, 0, 0); } while (0)
; #define PG8_LDA(dst, b, h) do { _Pragma("unroll") for (int m = 0; m < 4; ++m) _Pragma("unroll") for (int k = 0; k < 2; ++k) dst[m][k] = *(const PG8_LAS bf16x8*)(lds + PG8_SA(b, h) + aoff + m * 2048 + k * 1024); } while (0)
; #define PG8_LDB(dst, b, h) do { _Pragma("unroll") for (int n = 0; n < 2; ++n) _Pragma("unroll") for (int k = 0; k < 2; ++k) dst[n][k] = *(const PG8_LAS bf16x8*)(lds + PG8_SB(b, h) + boff + n * 2048 + k * 1024); } while (0)
; #define PG8_MMA(ai, bj, At, Bt) do { __builtin_amdgcn_s_setprio(1); _Pragma("unroll") for (int m = 0; m < 4; ++m) _Pragma("unroll") for (int n = 0; n < 2; ++n) _Pragma("unroll") for (int k = 0; k < 2; ++k) \
;         acc[ai][bj][m][n] = __builtin_amdgcn_mfma_f32_16x16x32_bf16(Bt[n][k], At[m][k], acc[ai][bj][m][n], 0, 0, 0); __builtin_amdgcn_s_setprio(0); } while (0)
; #define PG8_WAIT_V(n) asm volatile("s_waitcnt vmcnt(" #n ")" ::: "memory")
; #define PG8_WAIT_L(n) asm volatile("s_waitcnt lgkmcnt(" #n ")" ::: "memory")
; #define PG8_BAR __builtin_amdgcn_s_barrier()
; #define PG8_SCHED __builtin_amdgcn_sched_barrier(0)
; template <class Epi, class Sched, bool ALIGN_EPI = false, bool SP2 = false>
; __device__ __forceinline__ void gemm_phase(PG8_LAS unsigned char* lds, const Gemm g, const Sched& S, const Epi& E) {
;     ...
;             PG8_WAIT_V(8); PG8_WAIT_L(0); PG8_BAR; PG8_MMA(1, 0, At, B0); PG8_MMA(1, 1, At, B1); PG8_BAR; PG8_SCHED;
;             PG8_LDB(B0, 1, 0); PG8_LDB(B1, 1, 1); PG8_SCHED; PG8_LDA(At, 1, 0); PG8_STAGE(PG8_SA(0, 1), a2 + hstep, voffA);
;             PG8_WAIT_V(8); PG8_WAIT_L(0); PG8_BAR; PG8_MMA(0, 0, At, B0); PG8_MMA(0, 1, At, B1); PG8_BAR; PG8_SCHED;
	s_waitcnt lgkmcnt(0)
	v_mfma_f32_16x16x32_bf16 v[68:71], v[104:107], v[196:199], v[68:71]
	v_mfma_f32_16x16x32_bf16 v[60:63], v[144:147], v[196:199], v[60:63]
	v_mfma_f32_16x16x32_bf16 v[52:55], v[104:107], v[218:221], v[52:55]
	s_mov_b32 m0, s44
	v_mfma_f32_16x16x32_bf16 v[44:47], v[144:147], v[218:221], v[44:47]
	s_setprio 1
	global_load_lds_dwordx4 v[242:243], off
	v_mfma_f32_16x16x32_bf16 v[36:39], v[104:107], v[226:229], v[36:39]
	v_mfma_f32_16x16x32_bf16 v[28:31], v[144:147], v[226:229], v[28:31]
	v_mfma_f32_16x16x32_bf16 v[20:23], v[104:107], v[234:237], v[20:23]
	v_mfma_f32_16x16x32_bf16 v[12:15], v[144:147], v[234:237], v[12:15]
	v_mfma_f32_16x16x32_bf16 v[68:71], v[140:143], v[214:217], v[68:71]
	v_mfma_f32_16x16x32_bf16 v[60:63], v[148:151], v[214:217], v[60:63]
	v_mfma_f32_16x16x32_bf16 v[52:55], v[140:143], v[222:225], v[52:55]
	s_mov_b32 m0, s45
	v_mfma_f32_16x16x32_bf16 v[44:47], v[148:151], v[222:225], v[44:47]
	global_load_lds_dwordx4 v[244:245], off
	v_mfma_f32_16x16x32_bf16 v[36:39], v[140:143], v[230:233], v[36:39]
	v_mfma_f32_16x16x32_bf16 v[28:31], v[148:151], v[230:233], v[28:31]
	v_mfma_f32_16x16x32_bf16 v[20:23], v[140:143], v[238:241], v[20:23]
	v_mfma_f32_16x16x32_bf16 v[12:15], v[148:151], v[238:241], v[12:15]
	s_setprio 0
	s_setprio 1
	v_mfma_f32_16x16x32_bf16 v[64:67], v[152:155], v[196:199], v[64:67]
	v_mfma_f32_16x16x32_bf16 v[56:59], v[160:163], v[196:199], v[56:59]
	v_mfma_f32_16x16x32_bf16 v[48:51], v[152:155], v[218:221], v[48:51]
	v_mfma_f32_16x16x32_bf16 v[40:43], v[160:163], v[218:221], v[40:43]
	v_mfma_f32_16x16x32_bf16 v[32:35], v[152:155], v[226:229], v[32:35]
	v_mfma_f32_16x16x32_bf16 v[24:27], v[160:163], v[226:229], v[24:27]
	v_mfma_f32_16x16x32_bf16 v[16:19], v[152:155], v[234:237], v[16:19]
	v_mfma_f32_16x16x32_bf16 v[8:11], v[160:163], v[234:237], v[8:11]
	v_mfma_f32_16x16x32_bf16 v[64:67], v[156:159], v[214:217], v[64:67]
	v_mfma_f32_16x16x32_bf16 v[56:59], v[192:195], v[214:217], v[56:59]
	v_mfma_f32_16x16x32_bf16 v[48:51], v[156:159], v[222:225], v[48:51]
	v_mfma_f32_16x16x32_bf16 v[40:43], v[192:195], v[222:225], v[40:43]
	s_barrier
	v_mfma_f32_16x16x32_bf16 v[32:35], v[156:159], v[230:233], v[32:35]
	v_mfma_f32_16x16x32_bf16 v[24:27], v[192:195], v[230:233], v[24:27]
	v_mfma_f32_16x16x32_bf16 v[16:19], v[156:159], v[238:241], v[16:19]
	v_mfma_f32_16x16x32_bf16 v[8:11], v[192:195], v[238:241], v[8:11]
	s_setprio 0
	s_add_i32 s18, 0, 0x18000
	v_add_u32_e32 v0, s18, v210
	ds_read_b128 v[104:107], v0
	ds_read_b128 v[140:143], v0 offset:1024
	ds_read_b128 v[144:147], v0 offset:2048
	ds_read_b128 v[148:151], v0 offset:3072
	v_add_u32_e32 v0, s33, v210
	ds_read_b128 v[152:155], v0
	ds_read_b128 v[156:159], v0 offset:1024
	ds_read_b128 v[160:163], v0 offset:2048
	ds_read_b128 v[192:195], v0 offset:3072
	s_add_u32 s16, s42, 0x40000
	s_addc_u32 s17, s43, 0
	s_mov_b32 m0, s46
	v_lshl_add_u64 v[246:247], s[16:17], 0, v[184:185]
	ds_read_b128 v[196:199], v212 offset:32768
	ds_read_b128 v[214:217], v212 offset:33792
	ds_read_b128 v[218:221], v212 offset:34816
	ds_read_b128 v[222:225], v212 offset:35840
	ds_read_b128 v[226:229], v212 offset:36864
	ds_read_b128 v[230:233], v212 offset:37888
	ds_read_b128 v[234:237], v212 offset:38912
	ds_read_b128 v[238:241], v212 offset:39936
	global_load_lds_dwordx4 v[246:247], off
	v_lshl_add_u64 v[246:247], s[16:17], 0, v[180:181]
	s_mov_b32 m0, s47
	s_nop 0
	global_load_lds_dwordx4 v[246:247], off
	s_waitcnt vmcnt(8)
	s_waitcnt lgkmcnt(0)
	s_barrier
	s_waitcnt lgkmcnt(0)
	v_mfma_f32_16x16x32_bf16 v[136:139], v[104:107], v[196:199], v[136:139]
	v_mfma_f32_16x16x32_bf16 v[128:131], v[144:147], v[196:199], v[128:131]
	v_mfma_f32_16x16x32_bf16 v[120:123], v[104:107], v[218:221], v[120:123]
	v_mfma_f32_16x16x32_bf16 v[112:115], v[144:147], v[218:221], v[112:115]
	s_setprio 1
	v_mfma_f32_16x16x32_bf16 v[100:103], v[104:107], v[226:229], v[100:103]
	v_mfma_f32_16x16x32_bf16 v[92:95], v[144:147], v[226:229], v[92:95]
	v_mfma_f32_16x16x32_bf16 v[84:87], v[104:107], v[234:237], v[84:87]
	v_mfma_f32_16x16x32_bf16 v[76:79], v[144:147], v[234:237], v[76:79]
	v_mfma_f32_16x16x32_bf16 v[136:139], v[140:143], v[214:217], v[136:139]
	v_mfma_f32_16x16x32_bf16 v[128:131], v[148:151], v[214:217], v[128:131]
	v_mfma_f32_16x16x32_bf16 v[120:123], v[140:143], v[222:225], v[120:123]
	v_mfma_f32_16x16x32_bf16 v[112:115], v[148:151], v[222:225], v[112:115]
	v_mfma_f32_16x16x32_bf16 v[100:103], v[140:143], v[230:233], v[100:103]
	v_mfma_f32_16x16x32_bf16 v[92:95], v[148:151], v[230:233], v[92:95]
	v_mfma_f32_16x16x32_bf16 v[84:87], v[140:143], v[238:241], v[84:87]
	v_mfma_f32_16x16x32_bf16 v[76:79], v[148:151], v[238:241], v[76:79]
	s_setprio 0
	s_setprio 1
	v_mfma_f32_16x16x32_bf16 v[132:135], v[152:155], v[196:199], v[132:135]
	v_mfma_f32_16x16x32_bf16 v[124:127], v[160:163], v[196:199], v[124:127]
	v_mfma_f32_16x16x32_bf16 v[116:119], v[152:155], v[218:221], v[116:119]
	v_mfma_f32_16x16x32_bf16 v[108:111], v[160:163], v[218:221], v[108:111]
	v_mfma_f32_16x16x32_bf16 v[96:99], v[152:155], v[226:229], v[96:99]
	v_mfma_f32_16x16x32_bf16 v[88:91], v[160:163], v[226:229], v[88:91]
	v_mfma_f32_16x16x32_bf16 v[80:83], v[152:155], v[234:237], v[80:83]
	v_mfma_f32_16x16x32_bf16 v[72:75], v[160:163], v[234:237], v[72:75]
	v_mfma_f32_16x16x32_bf16 v[132:135], v[156:159], v[214:217], v[132:135]
	v_mfma_f32_16x16x32_bf16 v[124:127], v[192:195], v[214:217], v[124:127]
	v_mfma_f32_16x16x32_bf16 v[116:119], v[156:159], v[222:225], v[116:119]
	v_mfma_f32_16x16x32_bf16 v[108:111], v[192:195], v[222:225], v[108:111]
	s_barrier
; #define PG8_STAGE(bufoff, gbase, voff) do { _Pragma("unroll") for (int _i = 0; _i < 2; ++_i) \
;         __builtin_amdgcn_global_load_lds((const unsigned*)((const char*)(gbase) + (voff)[_i]), (PG8_LAS unsigned*)(lds + (bufoff) + ldsw + _i * 8192), 16, 0, 0); } while (0)
; #define PG8_LDA(dst, b, h) do { _Pragma("unroll") for (int m = 0; m < 4; ++m) _Pragma("unroll") for (int k = 0; k < 2; ++k) dst[m][k] = *(const PG8_LAS bf16x8*)(lds + PG8_SA(b, h) + aoff + m * 2048 + k * 1024); } while (0)
; #define PG8_MMA(ai, bj, At, Bt) do { __builtin_amdgcn_s_setprio(1); _Pragma("unroll") for (int m = 0; m < 4; ++m) _Pragma("unroll") for (int n = 0; n < 2; ++n) _Pragma("unroll") for (int k = 0; k < 2; ++k) \
;         acc[ai][bj][m][n] = __builtin_amdgcn_mfma_f32_16x16x32_bf16(Bt[n][k], At[m][k], acc[ai][bj][m][n], 0, 0, 0); __builtin_amdgcn_s_setprio(0); } while (0)
; #define PG8_WAIT_V(n) asm volatile("s_waitcnt vmcnt(" #n ")" ::: "memory")
; #define PG8_WAIT_L(n) asm volatile("s_waitcnt lgkmcnt(" #n ")" ::: "memory")
; #define PG8_BAR __builtin_amdgcn_s_barrier()
; #define PG8_SCHED __builtin_amdgcn_sched_barrier(0)
; template <class Epi, class Sched, bool ALIGN_EPI = false, bool SP2 = false>
; __device__ __forceinline__ void gemm_phase(PG8_LAS unsigned char* lds, const Gemm g, const Sched& S, const Epi& E) {
;     ...
;             PG8_WAIT_V(8); PG8_WAIT_L(0); PG8_BAR; PG8_MMA(0, 0, At, B0); PG8_MMA(0, 1, At, B1); PG8_BAR; PG8_SCHED;
;             PG8_LDA(At, 1, 1); PG8_STAGE(PG8_SB(1, 0), b3, voffB); PG8_STAGE(PG8_SB(1, 1), b3 + hstep, voffB); PG8_STAGE(PG8_SA(1, 0), a3, voffA);
;             PG8_WAIT_V(8); PG8_WAIT_L(0); PG8_BAR; PG8_MMA(1, 0, At, B0); PG8_MMA(1, 1, At, B1); PG8_BAR; PG8_SCHED;
	v_mfma_f32_16x16x32_bf16 v[96:99], v[156:159], v[230:233], v[96:99]
	v_mfma_f32_16x16x32_bf16 v[88:91], v[192:195], v[230:233], v[88:91]
	v_mfma_f32_16x16x32_bf16 v[80:83], v[156:159], v[238:241], v[80:83]
	v_mfma_f32_16x16x32_bf16 v[72:75], v[192:195], v[238:241], v[72:75]
	s_setprio 0
	s_add_i32 s16, s18, s36
	v_lshl_add_u64 v[2:3], v[2:3], 0, s[20:21]
	s_mov_b32 m0, s16
	ds_read_b128 v[196:199], v212 offset:49152
	ds_read_b128 v[214:217], v212 offset:50176
	ds_read_b128 v[218:221], v212 offset:51200
	ds_read_b128 v[222:225], v212 offset:52224
	ds_read_b128 v[226:229], v212 offset:53248
	ds_read_b128 v[230:233], v212 offset:54272
	ds_read_b128 v[234:237], v212 offset:55296
	ds_read_b128 v[238:241], v212 offset:56320
	global_load_lds_dwordx4 v[2:3], off
	s_add_i32 m0, s16, 0x2000
	s_add_u32 s16, s40, 0x40080
	v_lshl_add_u64 v[2:3], v[200:201], 0, s[20:21]
	s_addc_u32 s17, s41, 0
	s_add_i32 s18, s33, s36
	global_load_lds_dwordx4 v[2:3], off
	v_lshl_add_u64 v[2:3], s[16:17], 0, v[182:183]
	s_mov_b32 m0, s18
	s_nop 0
	global_load_lds_dwordx4 v[2:3], off
	v_lshl_add_u64 v[2:3], s[16:17], 0, v[178:179]
	s_add_i32 m0, s18, 0x2000
	s_nop 0
	global_load_lds_dwordx4 v[2:3], off
	v_lshl_add_u64 v[2:3], v[242:243], 0, s[20:21]
	v_lshl_add_u64 v[244:245], v[244:245], 0, s[20:21]
	s_waitcnt vmcnt(6)
	s_waitcnt lgkmcnt(0)
	s_barrier
	s_waitcnt lgkmcnt(0)
	v_mfma_f32_16x16x32_bf16 v[68:71], v[104:107], v[196:199], v[68:71]
	v_mfma_f32_16x16x32_bf16 v[60:63], v[144:147], v[196:199], v[60:63]
	v_mfma_f32_16x16x32_bf16 v[52:55], v[104:107], v[218:221], v[52:55]
	s_mov_b32 m0, s48
	v_mfma_f32_16x16x32_bf16 v[44:47], v[144:147], v[218:221], v[44:47]
	s_setprio 1
	global_load_lds_dwordx4 v[2:3], off
	v_mfma_f32_16x16x32_bf16 v[36:39], v[104:107], v[226:229], v[36:39]
	v_mfma_f32_16x16x32_bf16 v[28:31], v[144:147], v[226:229], v[28:31]
	v_mfma_f32_16x16x32_bf16 v[20:23], v[104:107], v[234:237], v[20:23]
	v_mfma_f32_16x16x32_bf16 v[12:15], v[144:147], v[234:237], v[12:15]
	v_mfma_f32_16x16x32_bf16 v[68:71], v[140:143], v[214:217], v[68:71]
	v_mfma_f32_16x16x32_bf16 v[60:63], v[148:151], v[214:217], v[60:63]
	v_mfma_f32_16x16x32_bf16 v[52:55], v[140:143], v[222:225], v[52:55]
	s_mov_b32 m0, s49
	v_mfma_f32_16x16x32_bf16 v[44:47], v[148:151], v[222:225], v[44:47]
	global_load_lds_dwordx4 v[244:245], off
	v_mfma_f32_16x16x32_bf16 v[36:39], v[140:143], v[230:233], v[36:39]
	v_mfma_f32_16x16x32_bf16 v[28:31], v[148:151], v[230:233], v[28:31]
	v_mfma_f32_16x16x32_bf16 v[20:23], v[140:143], v[238:241], v[20:23]
	v_mfma_f32_16x16x32_bf16 v[12:15], v[148:151], v[238:241], v[12:15]
	s_setprio 0
	s_setprio 1
	v_mfma_f32_16x16x32_bf16 v[64:67], v[152:155], v[196:199], v[64:67]
	v_mfma_f32_16x16x32_bf16 v[56:59], v[160:163], v[196:199], v[56:59]
	v_mfma_f32_16x16x32_bf16 v[48:51], v[152:155], v[218:221], v[48:51]
	v_mfma_f32_16x16x32_bf16 v[40:43], v[160:163], v[218:221], v[40:43]
	v_mfma_f32_16x16x32_bf16 v[32:35], v[152:155], v[226:229], v[32:35]
	v_mfma_f32_16x16x32_bf16 v[24:27], v[160:163], v[226:229], v[24:27]
	v_mfma_f32_16x16x32_bf16 v[16:19], v[152:155], v[234:237], v[16:19]
	v_mfma_f32_16x16x32_bf16 v[8:11], v[160:163], v[234:237], v[8:11]
	v_mfma_f32_16x16x32_bf16 v[64:67], v[156:159], v[214:217], v[64:67]
	v_mfma_f32_16x16x32_bf16 v[56:59], v[192:195], v[214:217], v[56:59]
	v_mfma_f32_16x16x32_bf16 v[48:51], v[156:159], v[222:225], v[48:51]
	v_mfma_f32_16x16x32_bf16 v[40:43], v[192:195], v[222:225], v[40:43]
	s_barrier
	v_mfma_f32_16x16x32_bf16 v[32:35], v[156:159], v[230:233], v[32:35]
	v_mfma_f32_16x16x32_bf16 v[24:27], v[192:195], v[230:233], v[24:27]
	v_mfma_f32_16x16x32_bf16 v[16:19], v[156:159], v[238:241], v[16:19]
	v_mfma_f32_16x16x32_bf16 v[8:11], v[192:195], v[238:241], v[8:11]
	s_setprio 0
	s_add_i32 s55, s55, 2
	s_add_u32 s8, s8, 0x100
	s_addc_u32 s9, s9, 0
	s_add_u32 s53, s53, 0x100
	s_addc_u32 s54, s54, 0
	s_cmp_gt_u32 s55, 13
	s_cbranch_scc0 .LBB0_257
	s_and_b64 vcc, exec, s[10:11]
	s_cbranch_vccz .LBB0_260
	s_barrier
	s_setprio 1
